# mirror of the static mixer priority: waves 0-3 raised instead of 4-7
# baseline (speedup 1.0000x reference)
; #define LAS __attribute__((address_space(3)))
; #define WAVE_ITEM_LOOP(COND, CALL) do { \
;         for (int it = blockIdx.x * 8 + wave; it < BATCH * NCH * 16; it += gridDim.x * 8) { \
;             const int bc = it >> 4, k = ((it & 15) + (it >> 8) + 4 * (it >> 11)) & 15, b = bc / NCH, ck_ = bc % NCH; if (!(COND)) continue; \
;             int lane = c.tid & 63; asm volatile("" : "+v"(lane)); CALL; } } while (0)
; template <int pass>
; __device__ __forceinline__ void mix_phase(const Args& a, const MixCtx& c) {
;     ...
;     const int wave = __builtin_amdgcn_readfirstlane(c.tid >> 6);
;     LAS unsigned char* wl = c.lds + wave * WLDS;
;     ...
; #pragma unroll 1
;     for (int st = 0; st < 3; ++st) {
;         const int kind = (st + (wave >> 2)) % 3;
;         if (kind == 0) { if (pass == 1) WAVE_ITEM_LOOP(k >= 8 && k < 12, w_ret_m1(c.ws, c.proj, wl, b, ck_, k - 8, lane)); else WAVE_ITEM_LOOP(k >= 8 && k < 12, w_ret_m3(a, c.l, c.ws, c.proj, c.y, wl, b, ck_, k - 8, lane)); }
;         else if (kind == 1) { if (pass == 1) WAVE_ITEM_LOOP(k >= 12, w_hg_m1(a, c.l, c.ws, c.proj, wl, b, ck_, k - 12, lane)); else WAVE_ITEM_LOOP(k >= 12, w_hg_m3(a, c.l, c.ws, c.proj, c.y, wl, b, ck_, k - 12, lane)); }
;         else { if (pass == 1) WAVE_ITEM_LOOP(k < 8, w_lru_m1(a, c.l, c.ws, c.proj, c.y, wl, b, ck_, k, lane)); else WAVE_ITEM_LOOP(k < 8, w_lru_m3(c.ws, c.proj, c.y, b, ck_, k, lane)); }
.LBB0_167:
	s_cmp_lt_i32 s2, 2
	s_mov_b64 s[4:5], -1
	s_cbranch_scc1 .LBB0_500
	s_load_dwordx4 s[48:51], s[0:1], 0xa0
	s_cmp_lg_u32 s2, 2
	v_readlane_b32 s80, v255, 20
	v_readlane_b32 s81, v255, 21
	s_mov_b32 s91, 0x8000
	s_movk_i32 s92, 0x7fff
	s_movk_i32 s93, 0xf000
	s_movk_i32 s96, 0x80
	s_mov_b32 s97, 0xc000
	s_mov_b32 s47, 0x24000
	s_mov_b32 s52, 0x3c000
	s_mov_b32 s53, 0x5040100
	s_cbranch_scc0 .LBB0_481
	v_readfirstlane_b32 s3, v220
	s_ashr_i32 s6, s3, 6
	s_cmp_ge_u32 s6, 4
	s_cbranch_scc1 .Lprio_m3_done
	s_setprio 1

; #define LAS __attribute__((address_space(3)))
; #define WAVE_ITEM_LOOP(COND, CALL) do { \
;         for (int it = blockIdx.x * 8 + wave; it < BATCH * NCH * 16; it += gridDim.x * 8) { \
;             const int bc = it >> 4, k = ((it & 15) + (it >> 8) + 4 * (it >> 11)) & 15, b = bc / NCH, ck_ = bc % NCH; if (!(COND)) continue; \
;             int lane = c.tid & 63; asm volatile("" : "+v"(lane)); CALL; } } while (0)
; template <int pass>
; __device__ __forceinline__ void mix_phase(const Args& a, const MixCtx& c) {
;     ...
;     const int wave = __builtin_amdgcn_readfirstlane(c.tid >> 6);
;     LAS unsigned char* wl = c.lds + wave * WLDS;
;     ...
; #pragma unroll 1
;     for (int st = 0; st < 3; ++st) {
;         const int kind = (st + (wave >> 2)) % 3;
;         if (kind == 0) { if (pass == 1) WAVE_ITEM_LOOP(k >= 8 && k < 12, w_ret_m1(c.ws, c.proj, wl, b, ck_, k - 8, lane)); else WAVE_ITEM_LOOP(k >= 8 && k < 12, w_ret_m3(a, c.l, c.ws, c.proj, c.y, wl, b, ck_, k - 8, lane)); }
;         else if (kind == 1) { if (pass == 1) WAVE_ITEM_LOOP(k >= 12, w_hg_m1(a, c.l, c.ws, c.proj, wl, b, ck_, k - 12, lane)); else WAVE_ITEM_LOOP(k >= 12, w_hg_m3(a, c.l, c.ws, c.proj, c.y, wl, b, ck_, k - 12, lane)); }
;         else { if (pass == 1) WAVE_ITEM_LOOP(k < 8, w_lru_m1(a, c.l, c.ws, c.proj, c.y, wl, b, ck_, k, lane)); else WAVE_ITEM_LOOP(k < 8, w_lru_m3(c.ws, c.proj, c.y, b, ck_, k, lane)); }
.LBB0_500:
	s_andn2_b64 vcc, exec, s[4:5]
	s_cbranch_vccnz .LBB0_824
	v_readfirstlane_b32 s2, v220
	s_ashr_i32 s3, s2, 6
	s_cmp_ge_u32 s3, 4
	s_cbranch_scc1 .Lprio_m1_done
	s_setprio 1
